# ph_up kloop: glds pieces interleaved after each 4-MFMA group of k-step 0 (ds_reads first)
# speedup vs baseline: 1.0077x; 1.0077x over previous
.LBB0_34:
	s_and_b32 s68, s25, 1
	s_lshl_b32 s29, s68, 16
	s_cmp_lt_u32 s25, 15
	s_cbranch_scc0 .LBB0_33
	s_add_i32 s12, s29, 0
	v_add3_u32 v189, s12, v145, v146
	ds_read_b128 v[156:159], v189 offset:32768
	ds_read_b128 v[160:163], v189 offset:34816
	ds_read_b128 v[168:171], v189 offset:36864
	ds_read_b128 v[172:175], v189 offset:38912
	v_add3_u32 v202, s12, v145, v147
	ds_read_b128 v[164:167], v202
	v_add3_u32 v203, s12, v149, v148
	v_add3_u32 v204, s12, v149, v150
	v_add3_u32 v205, s12, v149, v151
	ds_read_b128 v[190:193], v203
	s_waitcnt lgkmcnt(1)
	v_mfma_f32_16x16x32_bf16 v[126:129], v[156:159], v[164:167], v[126:129]
	v_add3_u32 v206, s12, v149, v152
	v_add3_u32 v207, s12, v149, v153
	v_add3_u32 v208, s12, v149, v154
	v_mfma_f32_16x16x32_bf16 v[122:125], v[160:163], v[164:167], v[122:125]
	v_add3_u32 v209, s12, v149, v155
	s_add_i32 s25, s25, 1
	v_mfma_f32_16x16x32_bf16 v[118:121], v[168:171], v[164:167], v[118:121]
	v_mfma_f32_16x16x32_bf16 v[114:117], v[172:175], v[164:167], v[114:117]
	ds_read_b128 v[164:167], v204
	ds_read_b128 v[194:197], v205
	s_lshl_b32 s29, s68, 16
	s_xor_b32 s12, s29, 0x10000
	s_add_i32 s13, s12, s30
	s_mov_b32 m0, s13
	s_nop 0
	global_load_lds_dwordx4 v141, s[8:9]
	s_waitcnt lgkmcnt(2)
	v_mfma_f32_16x16x32_bf16 v[110:113], v[156:159], v[190:193], v[110:113]
	v_mfma_f32_16x16x32_bf16 v[106:109], v[160:163], v[190:193], v[106:109]
	v_mfma_f32_16x16x32_bf16 v[102:105], v[168:171], v[190:193], v[102:105]
	v_mfma_f32_16x16x32_bf16 v[98:101], v[172:175], v[190:193], v[98:101]
	ds_read_b128 v[190:193], v206
	ds_read_b128 v[198:201], v207
	s_add_i32 s12, s12, s65
	s_mov_b32 m0, s12
	s_nop 0
	global_load_lds_dwordx4 v140, s[10:11]
	s_waitcnt lgkmcnt(3)
	v_mfma_f32_16x16x32_bf16 v[94:97], v[156:159], v[164:167], v[94:97]
	v_mfma_f32_16x16x32_bf16 v[90:93], v[160:163], v[164:167], v[90:93]
	v_mfma_f32_16x16x32_bf16 v[86:89], v[168:171], v[164:167], v[86:89]
	v_mfma_f32_16x16x32_bf16 v[82:85], v[172:175], v[164:167], v[82:85]
	s_xor_b32 s12, s29, 0x12000
	s_add_i32 s13, s12, s30
	s_add_i32 s39, s12, s65
	s_mov_b32 m0, s13
	s_nop 0
	global_load_lds_dwordx4 v142, s[8:9]
	s_waitcnt lgkmcnt(2)
	v_mfma_f32_16x16x32_bf16 v[78:81], v[156:159], v[194:197], v[78:81]
	v_mfma_f32_16x16x32_bf16 v[74:77], v[160:163], v[194:197], v[74:77]
	v_mfma_f32_16x16x32_bf16 v[70:73], v[168:171], v[194:197], v[70:73]
	v_mfma_f32_16x16x32_bf16 v[66:69], v[172:175], v[194:197], v[66:69]
	ds_read_b128 v[164:167], v208
	ds_read_b128 v[194:197], v209
	s_add_u32 s12, s10, 0x20000
	s_addc_u32 s13, s11, 0
	s_mov_b32 m0, s39
	s_nop 0
	global_load_lds_dwordx4 v140, s[12:13]
	s_waitcnt lgkmcnt(3)
	v_mfma_f32_16x16x32_bf16 v[62:65], v[156:159], v[190:193], v[62:65]
	v_mfma_f32_16x16x32_bf16 v[58:61], v[160:163], v[190:193], v[58:61]
	v_mfma_f32_16x16x32_bf16 v[54:57], v[168:171], v[190:193], v[54:57]
	v_mfma_f32_16x16x32_bf16 v[50:53], v[172:175], v[190:193], v[50:53]
	s_xor_b32 s12, s29, 0x14000
	s_add_i32 s13, s12, s30
	s_add_i32 s39, s12, s65
	s_mov_b32 m0, s13
	s_nop 0
	global_load_lds_dwordx4 v143, s[8:9]
	s_waitcnt lgkmcnt(2)
	v_mfma_f32_16x16x32_bf16 v[46:49], v[156:159], v[198:201], v[46:49]
	v_mfma_f32_16x16x32_bf16 v[42:45], v[160:163], v[198:201], v[42:45]
	v_mfma_f32_16x16x32_bf16 v[38:41], v[168:171], v[198:201], v[38:41]
	v_mfma_f32_16x16x32_bf16 v[34:37], v[172:175], v[198:201], v[34:37]
	s_add_u32 s12, s10, 0x40000
	s_addc_u32 s13, s11, 0
	s_mov_b32 m0, s39
	s_nop 0
	global_load_lds_dwordx4 v140, s[12:13]
	s_waitcnt lgkmcnt(1)
	v_mfma_f32_16x16x32_bf16 v[30:33], v[156:159], v[164:167], v[30:33]
	v_mfma_f32_16x16x32_bf16 v[26:29], v[160:163], v[164:167], v[26:29]
	v_mfma_f32_16x16x32_bf16 v[22:25], v[168:171], v[164:167], v[22:25]
	v_mfma_f32_16x16x32_bf16 v[18:21], v[172:175], v[164:167], v[18:21]
	s_xor_b32 s12, s29, 0x16000
	s_add_i32 s13, s12, s30
	s_add_i32 s39, s12, s65
	s_mov_b32 m0, s13
	s_nop 0
	global_load_lds_dwordx4 v144, s[8:9]
	s_waitcnt lgkmcnt(0)
	v_mfma_f32_16x16x32_bf16 v[14:17], v[156:159], v[194:197], v[14:17]
	v_mfma_f32_16x16x32_bf16 v[10:13], v[160:163], v[194:197], v[10:13]
	v_mfma_f32_16x16x32_bf16 v[6:9], v[168:171], v[194:197], v[6:9]
	v_mfma_f32_16x16x32_bf16 v[2:5], v[172:175], v[194:197], v[2:5]
	ds_read_b128 v[156:159], v189 offset:33792
	ds_read_b128 v[160:163], v189 offset:35840
	ds_read_b128 v[168:171], v189 offset:37888
	ds_read_b128 v[172:175], v189 offset:39936
	ds_read_b128 v[164:167], v202 offset:1024
	ds_read_b128 v[190:193], v203 offset:1024
	s_add_u32 s12, s10, 0x60000
	s_addc_u32 s13, s11, 0
	s_mov_b32 m0, s39
	s_nop 0
	global_load_lds_dwordx4 v140, s[12:13]
	s_waitcnt lgkmcnt(1)
	v_mfma_f32_16x16x32_bf16 v[126:129], v[156:159], v[164:167], v[126:129]
	v_mfma_f32_16x16x32_bf16 v[122:125], v[160:163], v[164:167], v[122:125]
	v_mfma_f32_16x16x32_bf16 v[118:121], v[168:171], v[164:167], v[118:121]
	v_mfma_f32_16x16x32_bf16 v[114:117], v[172:175], v[164:167], v[114:117]
	ds_read_b128 v[164:167], v204 offset:1024
	ds_read_b128 v[194:197], v205 offset:1024
	s_waitcnt lgkmcnt(2)
	v_mfma_f32_16x16x32_bf16 v[110:113], v[156:159], v[190:193], v[110:113]
	v_mfma_f32_16x16x32_bf16 v[106:109], v[160:163], v[190:193], v[106:109]
	v_mfma_f32_16x16x32_bf16 v[102:105], v[168:171], v[190:193], v[102:105]
	v_mfma_f32_16x16x32_bf16 v[98:101], v[172:175], v[190:193], v[98:101]
	ds_read_b128 v[190:193], v206 offset:1024
	ds_read_b128 v[198:201], v207 offset:1024
	s_waitcnt lgkmcnt(3)
	v_mfma_f32_16x16x32_bf16 v[94:97], v[156:159], v[164:167], v[94:97]
	v_mfma_f32_16x16x32_bf16 v[90:93], v[160:163], v[164:167], v[90:93]
	v_mfma_f32_16x16x32_bf16 v[86:89], v[168:171], v[164:167], v[86:89]
	v_mfma_f32_16x16x32_bf16 v[82:85], v[172:175], v[164:167], v[82:85]
	s_waitcnt lgkmcnt(2)
	v_mfma_f32_16x16x32_bf16 v[78:81], v[156:159], v[194:197], v[78:81]
	v_mfma_f32_16x16x32_bf16 v[74:77], v[160:163], v[194:197], v[74:77]
	v_mfma_f32_16x16x32_bf16 v[70:73], v[168:171], v[194:197], v[70:73]
	v_mfma_f32_16x16x32_bf16 v[66:69], v[172:175], v[194:197], v[66:69]
	ds_read_b128 v[164:167], v208 offset:1024
	ds_read_b128 v[194:197], v209 offset:1024
	s_waitcnt lgkmcnt(3)
	v_mfma_f32_16x16x32_bf16 v[62:65], v[156:159], v[190:193], v[62:65]
	v_mfma_f32_16x16x32_bf16 v[58:61], v[160:163], v[190:193], v[58:61]
	v_mfma_f32_16x16x32_bf16 v[54:57], v[168:171], v[190:193], v[54:57]
	v_mfma_f32_16x16x32_bf16 v[50:53], v[172:175], v[190:193], v[50:53]
	s_waitcnt lgkmcnt(2)
	v_mfma_f32_16x16x32_bf16 v[46:49], v[156:159], v[198:201], v[46:49]
	v_mfma_f32_16x16x32_bf16 v[42:45], v[160:163], v[198:201], v[42:45]
	v_mfma_f32_16x16x32_bf16 v[38:41], v[168:171], v[198:201], v[38:41]
	v_mfma_f32_16x16x32_bf16 v[34:37], v[172:175], v[198:201], v[34:37]
	s_waitcnt lgkmcnt(1)
	v_mfma_f32_16x16x32_bf16 v[30:33], v[156:159], v[164:167], v[30:33]
	v_mfma_f32_16x16x32_bf16 v[26:29], v[160:163], v[164:167], v[26:29]
	v_mfma_f32_16x16x32_bf16 v[22:25], v[168:171], v[164:167], v[22:25]
	v_mfma_f32_16x16x32_bf16 v[18:21], v[172:175], v[164:167], v[18:21]
	s_waitcnt lgkmcnt(0)
	v_mfma_f32_16x16x32_bf16 v[14:17], v[156:159], v[194:197], v[14:17]
	v_mfma_f32_16x16x32_bf16 v[10:13], v[160:163], v[194:197], v[10:13]
	v_mfma_f32_16x16x32_bf16 v[6:9], v[168:171], v[194:197], v[6:9]
	v_mfma_f32_16x16x32_bf16 v[2:5], v[172:175], v[194:197], v[2:5]
	s_add_u32 s10, s10, 0x80
	s_addc_u32 s11, s11, 0
	s_waitcnt vmcnt(0)
	s_add_u32 s8, s8, 0x80
	s_addc_u32 s9, s9, 0
	s_cmp_lg_u32 s25, 16
	s_barrier
	s_cbranch_scc0 .LBB0_38
	s_branch .LBB0_34
